# K-loop head pinned to a 64-byte boundary (.p2align 6; was at offset 12 mod 64, 4 mod 8)
# baseline (speedup 1.0000x reference)
; template <class Epi, class Sched, bool ALIGN_EPI = false, bool SP2 = false>
; __device__ __forceinline__ void gemm_phase(PG8_LAS unsigned char* lds, const Gemm g, const Sched& S, const Epi& E) {
;     ...
;     f32x4 acc[2][2][4][2];
; #pragma unroll
;     for (int a = 0; a < 2; ++a)
; #pragma unroll
;         for (int b = 0; b < 2; ++b)
; #pragma unroll
;             for (int m = 0; m < 4; ++m)
; #pragma unroll
;                 for (int n = 0; n < 2; ++n) acc[a][b][m][n] = (f32x4){0.f, 0.f, 0.f, 0.f};
.Lpf_skip:
	v_add_u32_e32 v242, 0x10000, v228
	v_add_u32_e32 v243, 0x14000, v228
	v_add_u32_e32 v244, 0x18000, v228
	v_add_u32_e32 v245, 0x1c000, v228
	v_mov_b64_e32 v[2:3], 0
	v_mov_b64_e32 v[4:5], 0
	v_mov_b64_e32 v[6:7], 0
	v_mov_b64_e32 v[8:9], 0
	v_mov_b64_e32 v[10:11], 0
	v_mov_b64_e32 v[12:13], 0
	v_mov_b64_e32 v[14:15], 0
	v_mov_b64_e32 v[16:17], 0
	v_mov_b64_e32 v[18:19], 0
	v_mov_b64_e32 v[20:21], 0
	v_mov_b64_e32 v[22:23], 0
	v_mov_b64_e32 v[24:25], 0
	v_mov_b64_e32 v[26:27], 0
	v_mov_b64_e32 v[28:29], 0
	v_mov_b64_e32 v[30:31], 0
	v_mov_b64_e32 v[32:33], 0
	v_mov_b64_e32 v[34:35], 0
	v_mov_b64_e32 v[36:37], 0
	v_mov_b64_e32 v[38:39], 0
	v_mov_b64_e32 v[40:41], 0
	v_mov_b64_e32 v[42:43], 0
	v_mov_b64_e32 v[44:45], 0
	v_mov_b64_e32 v[46:47], 0
	v_mov_b64_e32 v[48:49], 0
	v_mov_b64_e32 v[50:51], 0
	v_mov_b64_e32 v[52:53], 0
	v_mov_b64_e32 v[54:55], 0
	v_mov_b64_e32 v[56:57], 0
	v_mov_b64_e32 v[58:59], 0
	v_mov_b64_e32 v[60:61], 0
	v_mov_b64_e32 v[62:63], 0
	v_mov_b64_e32 v[64:65], 0
	v_mov_b64_e32 v[66:67], 0
	v_mov_b64_e32 v[68:69], 0
	v_mov_b64_e32 v[70:71], 0
	v_mov_b64_e32 v[72:73], 0
	v_mov_b64_e32 v[74:75], 0
	v_mov_b64_e32 v[76:77], 0
	v_mov_b64_e32 v[78:79], 0
	v_mov_b64_e32 v[80:81], 0
	v_mov_b64_e32 v[82:83], 0
	v_mov_b64_e32 v[84:85], 0
	v_mov_b64_e32 v[86:87], 0
	v_mov_b64_e32 v[88:89], 0
	v_mov_b64_e32 v[90:91], 0
	v_mov_b64_e32 v[92:93], 0
	v_mov_b64_e32 v[94:95], 0
	v_mov_b64_e32 v[96:97], 0
	v_mov_b64_e32 v[98:99], 0
	v_mov_b64_e32 v[100:101], 0
	v_mov_b64_e32 v[102:103], 0
	v_mov_b64_e32 v[104:105], 0
	v_mov_b64_e32 v[106:107], 0
	v_mov_b64_e32 v[108:109], 0
	v_mov_b64_e32 v[110:111], 0
	v_mov_b64_e32 v[112:113], 0
	v_mov_b64_e32 v[114:115], 0
	v_mov_b64_e32 v[116:117], 0
	v_mov_b64_e32 v[118:119], 0
	v_mov_b64_e32 v[120:121], 0
	v_mov_b64_e32 v[122:123], 0
	v_mov_b64_e32 v[124:125], 0
	v_mov_b64_e32 v[126:127], 0
	v_mov_b64_e32 v[128:129], 0
	.p2align	6
